# prologue: the S5 discretisation (f64 math on 32 workgroups) runs first instead of last so its latency hides under the bandwidth-bound transposes of the other workgroups
# speedup vs baseline: 1.0337x; 1.0022x over previous
.LBB0_23:
	s_or_b64 exec, exec, s[4:5]
	s_mov_b32 s100, s2
	s_mov_b32 s101, s13
	s_mov_b64 s[20:21], s[66:67]
	v_mov_b32_e32 v65, v247
	s_mov_b32 s26, s2
	s_mov_b32 s25, s13
	s_load_dwordx2 s[14:15], s[20:21], 0xb0
	v_readfirstlane_b32 s0, v65
	s_ashr_i32 s24, s0, 6
	s_lshl_b32 s0, s26, 3
	v_and_b32_e32 v69, 63, v65
	s_add_i32 s0, s0, s24
	s_lshl_b32 s12, s25, 3
	v_lshlrev_b32_e32 v64, 2, v69
	s_cmpk_gt_i32 s0, 0xff
	v_writelane_b32 v253, s66, 0
	s_nop 1
	v_writelane_b32 v253, s67, 1
	v_writelane_b32 v253, s68, 2
	s_nop 1
	v_writelane_b32 v253, s69, 3
	s_cbranch_scc1 .Ldisc_done
	s_waitcnt lgkmcnt(0)
	s_add_u32 s22, s14, 0x8340000
	s_addc_u32 s23, s15, 0
	s_load_dwordx8 s[4:11], s[20:21], 0x20
	s_load_dwordx4 s[16:19], s[20:21], 0x40
	s_load_dwordx2 s[2:3], s[20:21], 0x50
	s_lshl_b32 s1, s26, 9
	s_lshl_b32 s13, s24, 6
	s_add_i32 s1, s1, s13
	v_mov_b32_e32 v1, 0
	v_or_b32_e32 v2, s1, v69
	s_ashr_i32 s1, s0, 31
	s_ashr_i32 s13, s12, 31
	v_lshlrev_b32_e32 v0, 5, v69
	s_lshl_b32 s89, s25, 10
	s_lshl_b32 s90, s25, 9
	s_lshl_b64 s[20:21], s[0:1], 12
	v_mov_b32_e32 v65, v1
	s_lshl_b64 s[24:25], s[12:13], 12
	s_lshl_b64 s[26:27], s[0:1], 2
	v_lshl_add_u64 v[6:7], s[14:15], 0, v[64:65]
	s_waitcnt lgkmcnt(0)
	s_add_u32 s8, s8, s26
	v_lshl_add_u64 v[8:9], s[14:15], 0, v[0:1]
	v_lshl_add_u64 v[10:11], s[18:19], 0, v[64:65]
	s_mov_b32 s14, 0
	s_mov_b32 s19, 0x3fd55555
	s_mov_b32 s28, 0x55555555
	s_mov_b32 s34, 0x9999999a
	s_mov_b32 s36, 0x92492492
	s_mov_b32 s38, 0x1c71c71c
	s_mov_b32 s42, 0x745d1746
	s_mov_b32 s46, 0x13b13b14
	s_mov_b32 s50, 0x6dc9c883
	s_mov_b32 s52, 0x54442d18
	s_mov_b32 s54, 0x33145c07
	s_mov_b32 s58, 0x11111111
	s_mov_b32 s60, 0x18618618
	s_mov_b32 s66, 0x29e4129e
	s_mov_b32 s68, 0x16c16c17
	s_mov_b32 s70, 0xf07c1f08
	s_mov_b32 s72, 0x1a41a41a
	s_mov_b32 s74, 0x13813814
	s_mov_b32 s76, 0x16816817
	s_mov_b32 s80, 0x1e1e1e1e
	s_mov_b32 s82, 0xfd017f40
	s_mov_b32 s84, 0x1ac5701b
	v_lshlrev_b32_e32 v4, 1, v2
	s_addc_u32 s9, s9, s27
	s_lshl_b64 s[26:27], s[12:13], 2
	v_lshl_add_u64 v[12:13], s[2:3], 0, v[64:65]
	s_mov_b32 s15, 0x3f900000
	s_mov_b32 s29, 0x3fc55555
	s_mov_b32 s30, 0x55555555
	s_mov_b32 s31, s19
	s_mov_b32 s35, 0x3fc99999
	s_mov_b32 s37, 0x3fc24924
	s_mov_b32 s39, 0x3fbc71c7
	s_mov_b32 s41, 0x3fb99999
	s_mov_b32 s43, 0x3fb745d1
	s_mov_b32 s45, 0x3fb55555
	s_mov_b32 s47, 0x3fb3b13b
	s_mov_b32 s49, 0x3fb24924
	s_mov_b32 s51, 0x3fe45f30
	s_mov_b32 s53, 0xbff921fb
	s_mov_b32 s55, 0xbc91a626
	s_mov_b32 s57, 0x3fa99999
	s_mov_b32 s59, 0x3fa11111
	s_mov_b32 s61, 0x3f986186
	s_mov_b32 s63, 0x3f924924
	s_mov_b32 s65, 0x3f8c71c7
	s_mov_b32 s67, 0x3f829e41
	s_mov_b32 s69, 0x3f86c16c
	s_mov_b32 s71, 0x3f7f07c1
	s_mov_b32 s73, 0x3f7a41a4
	s_mov_b32 s75, 0x3f738138
	s_mov_b32 s77, 0x3f768168
	s_mov_b32 s79, 0x3f711111
	s_mov_b32 s81, 0x3f6e1e1e
	s_mov_b32 s83, 0x3f67f405
	s_mov_b32 s85, 0x3f6ac570
	s_movk_i32 s1, 0x7fff
	s_mov_b32 s13, 0xffff0000
	s_mov_b32 s91, 0x8360000
	s_mov_b32 s92, 0x8460000
	s_branch .LBB0_63

.Ldisc_done:
	s_mov_b32 s2, s100
	s_mov_b32 s13, s101
	s_mov_b64 s[20:21], s[66:67]
	v_mov_b32_e32 v65, v247
	s_mov_b32 s26, s2
	s_mov_b32 s25, s13
	s_load_dwordx2 s[14:15], s[20:21], 0xb0
	s_load_dwordx2 s[6:7], s[20:21], 0x8
	v_readfirstlane_b32 s0, v65
	s_ashr_i32 s24, s0, 6
	s_lshl_b32 s0, s26, 3
	v_and_b32_e32 v69, 63, v65
	s_add_i32 s0, s0, s24
	s_lshl_b32 s12, s25, 3
	s_cmpk_gt_i32 s0, 0xfff
	v_lshlrev_b32_e32 v64, 2, v69
	s_cbranch_scc1 .LBB0_49
	s_mul_i32 s1, s24, 0x4100
	v_lshrrev_b32_e32 v76, 4, v69
	v_and_b32_e32 v0, 60, v64
	s_add_i32 s1, s1, 0
	v_lshlrev_b32_e32 v1, 2, v0
	v_mul_u32_u24_e32 v2, 0x104, v76
	v_add3_u32 v77, s1, v1, v2
	v_lshlrev_b32_e32 v1, 3, v69
	v_lshrrev_b32_e32 v78, 3, v69
	v_and_b32_e32 v68, 56, v1
	v_mul_u32_u24_e32 v1, 0x104, v68
	v_lshlrev_b32_e32 v2, 2, v78
	v_add3_u32 v79, s1, v1, v2
	s_waitcnt lgkmcnt(0)
	s_add_u32 s1, s14, 0x5000000
	s_addc_u32 s3, s15, 0
	v_mov_b32_e32 v67, 0
	s_add_u32 s8, s6, 0x4000
	v_lshlrev_b32_e32 v66, 1, v68
	s_addc_u32 s9, s7, 0
	v_lshl_add_u64 v[2:3], s[14:15], 0, v[66:67]
	s_mov_b64 s[10:11], 0x4000000
	v_lshl_add_u64 v[70:71], v[2:3], 0, s[10:11]
	s_add_u32 s10, s6, 0x2000
	s_addc_u32 s11, s7, 0
	s_mov_b64 s[16:17], 0x2000000
	s_cmp_lg_u64 s[6:7], 0
	s_mov_b64 s[18:19], 0x7000000
	s_mov_b32 s5, 0
	v_or_b32_e32 v80, 8, v78
	v_or_b32_e32 v81, 16, v78
	v_or_b32_e32 v82, 24, v78
	v_or_b32_e32 v83, 32, v78
	v_or_b32_e32 v84, 40, v78
	v_or_b32_e32 v85, 48, v78
	v_or_b32_e32 v86, 56, v78
	v_lshl_add_u64 v[72:73], v[2:3], 0, s[16:17]
	s_cselect_b64 s[16:17], -1, 0
	v_lshl_add_u64 v[74:75], v[2:3], 0, s[18:19]
	s_mov_b32 s27, 0x8000
	s_mov_b32 s28, 0x10000
	s_mov_b32 s29, 0x18000
	s_mov_b32 s30, 0x20000
	s_mov_b32 s31, 0x28000
	s_mov_b32 s34, 0x30000
	s_mov_b32 s35, 0x38000
	s_mov_b32 s36, 0x40000
	s_mov_b32 s37, 0x48000
	s_mov_b32 s38, 0x50000
	s_mov_b32 s39, 0x58000
	s_mov_b32 s40, 0x60000
	s_mov_b32 s41, 0x68000
	s_mov_b32 s42, 0x70000
	s_mov_b32 s43, 0x78000
	v_add_u32_e32 v87, 0x410, v77
	v_add_u32_e32 v88, 0x418, v77
	v_add_u32_e32 v89, 0x820, v77
	v_add_u32_e32 v90, 0x828, v77
	v_add_u32_e32 v91, 0xc30, v77
	v_add_u32_e32 v92, 0xc38, v77
	v_add_u32_e32 v93, 0x1040, v77
	v_add_u32_e32 v94, 0x1048, v77
	v_add_u32_e32 v95, 0x1450, v77
	v_add_u32_e32 v96, 0x1458, v77
	v_add_u32_e32 v97, 0x1860, v77
	v_add_u32_e32 v98, 0x1868, v77
	v_add_u32_e32 v99, 0x1c70, v77
	v_add_u32_e32 v100, 0x1c78, v77
	v_add_u32_e32 v101, 0x2080, v77
	v_add_u32_e32 v102, 0x2088, v77
	v_add_u32_e32 v103, 0x2490, v77
	v_add_u32_e32 v104, 0x2498, v77
	v_add_u32_e32 v105, 0x28a0, v77
	v_add_u32_e32 v106, 0x28a8, v77
	v_add_u32_e32 v107, 0x2cb0, v77
	v_add_u32_e32 v108, 0x2cb8, v77
	v_add_u32_e32 v109, 0x30c0, v77
	v_add_u32_e32 v110, 0x30c8, v77
	v_add_u32_e32 v111, 0x34d0, v77
	v_add_u32_e32 v112, 0x34d8, v77
	v_add_u32_e32 v113, 0x38e0, v77
	v_add_u32_e32 v114, 0x38e8, v77
	v_add_u32_e32 v115, 0x3cf0, v77
	v_add_u32_e32 v116, 0x3cf8, v77
	s_movk_i32 s44, 0x7fff
	s_mov_b32 s45, 0xffff0000
	v_lshlrev_b32_e32 v66, 2, v0
	v_add_u32_e32 v117, 0x400, v79
	s_mov_b32 s46, s0
	s_branch .LBB0_27

.LBB0_59:
.LBB0_69:
	s_load_dwordx2 s[0:1], s[66:67], 0xb0
	s_getreg_b32 s4, hwreg(HW_REG_XCC_ID, 0, 4)
	s_waitcnt vmcnt(0)
	s_waitcnt lgkmcnt(0)
	s_barrier
	s_add_u32 s2, s0, 0x8560000
	v_writelane_b32 v253, s2, 4
	s_addc_u32 s2, s1, 0
	v_writelane_b32 v253, s2, 5
	s_and_saveexec_b64 s[2:3], s[68:69]
	s_cbranch_execz .LBB0_121
	s_add_i32 s5, 0, 0x23fc0
	v_mov_b32_e32 v0, s5
	s_waitcnt vmcnt(0) expcnt(0) lgkmcnt(0)
	ds_read_b32 v2, v0
	s_add_i32 s5, 0, 0x23fc4
	v_mov_b32_e32 v0, s5
	ds_read_b32 v0, v0
	s_and_b32 s46, s4, 15
	s_waitcnt lgkmcnt(1)
	v_cmp_ne_u32_e32 vcc, 0, v2
	s_cbranch_vccnz .LBB0_85
	s_add_u32 s4, s0, 0x8560200
	s_addc_u32 s5, s1, 0
	s_add_u32 s6, s0, 0x8560400
	s_addc_u32 s7, s1, 0
	s_add_u32 s8, s0, 0x8560500
	s_addc_u32 s9, s1, 0
	s_add_u32 s10, s0, 0x8560600
	s_addc_u32 s11, s1, 0
	s_add_u32 s12, s0, 0x8560700
	s_addc_u32 s13, s1, 0
	s_add_u32 s14, s0, 0x8560800
	s_addc_u32 s15, s1, 0
	s_add_u32 s16, s0, 0x8560900
	s_addc_u32 s17, s1, 0
	s_add_u32 s18, s0, 0x8560a00
	s_addc_u32 s19, s1, 0
	s_add_u32 s20, s0, 0x8560b00
	s_addc_u32 s21, s1, 0
	s_add_u32 s22, s0, 0x8560c00
	s_addc_u32 s23, s1, 0
	s_add_u32 s24, s0, 0x8560d00
	s_addc_u32 s25, s1, 0
	s_add_u32 s26, s0, 0x8560e00
	s_addc_u32 s27, s1, 0
	s_add_u32 s28, s0, 0x8560f00
	s_addc_u32 s29, s1, 0
	s_add_u32 s30, s0, 0x8561000
	s_addc_u32 s31, s1, 0
	s_add_u32 s34, s0, 0x8561100
	s_addc_u32 s35, s1, 0
	s_add_u32 s36, s0, 0x8561200
	s_addc_u32 s37, s1, 0
	s_add_u32 s38, s0, 0x8561300
	s_addc_u32 s39, s1, 0
	s_mov_b32 s47, 1
	v_mov_b32_e32 v16, 0
	s_movk_i32 s48, 0x100
	s_branch .LBB0_73
